# norm0: second load pair hoisted next to the first (one exposed latency per row instead of two); final norm: next-row prefetch
# speedup vs baseline: 1.0187x; 1.0045x over previous
.LBB0_20:
	v_lshl_add_u64 v[18:19], v[16:17], 0, v[32:33]
	global_load_dwordx4 v[22:25], v[18:19], off
	global_load_dwordx4 v[14:17], v[18:19], off offset:1024
	global_load_dwordx4 v[100:103], v[18:19], off offset:2048
	global_load_dwordx4 v[104:107], v[18:19], off offset:3072
	s_andn2_b64 vcc, exec, s[2:3]
	s_waitcnt vmcnt(3)
	v_mov_b32_e32 v26, v23
	s_waitcnt vmcnt(2)
	v_mov_b32_e32 v27, v15
	v_mov_b32_e32 v20, v22
	v_mov_b32_e32 v21, v14
	v_pk_mul_f32 v[26:27], v[26:27], v[26:27]
	s_nop 0
	v_pk_fma_f32 v[20:21], v[20:21], v[20:21], v[26:27]
	v_mov_b32_e32 v26, v24
	v_mov_b32_e32 v27, v16
	v_pk_fma_f32 v[20:21], v[26:27], v[26:27], v[20:21]
	v_mov_b32_e32 v26, v25
	v_mov_b32_e32 v27, v17
	v_pk_fma_f32 v[46:47], v[26:27], v[26:27], v[20:21]
	s_waitcnt vmcnt(1)
	v_mov_b32_e32 v26, v100
	v_mov_b32_e32 v27, v101
	v_mov_b32_e32 v28, v102
	v_mov_b32_e32 v29, v103
	s_waitcnt vmcnt(0)
	v_mov_b32_e32 v18, v104
	v_mov_b32_e32 v19, v105
	v_mov_b32_e32 v20, v106
	v_mov_b32_e32 v21, v107
	v_add_f32_e32 v46, v46, v47
	s_waitcnt vmcnt(1)
	v_mov_b32_e32 v50, v27
	s_waitcnt vmcnt(0)
	v_mov_b32_e32 v51, v19
	v_mov_b32_e32 v48, v26
	v_mov_b32_e32 v49, v18
	v_pk_mul_f32 v[50:51], v[50:51], v[50:51]
	s_nop 0
	v_pk_fma_f32 v[48:49], v[48:49], v[48:49], v[50:51]
	v_mov_b32_e32 v50, v28
	v_mov_b32_e32 v51, v20
	v_pk_fma_f32 v[48:49], v[50:51], v[50:51], v[48:49]
	v_mov_b32_e32 v50, v29
	v_mov_b32_e32 v51, v21
	v_pk_fma_f32 v[48:49], v[50:51], v[50:51], v[48:49]
	s_nop 0
	v_add_f32_e32 v46, v46, v48
	v_add_f32_e32 v46, v46, v49
	ds_bpermute_b32 v47, v40, v46
	s_waitcnt lgkmcnt(0)
	v_add_f32_e32 v46, v46, v47
	ds_bpermute_b32 v47, v41, v46
	s_waitcnt lgkmcnt(0)
	v_add_f32_e32 v46, v46, v47
	ds_bpermute_b32 v47, v42, v46
	s_waitcnt lgkmcnt(0)
	v_add_f32_e32 v46, v46, v47
	ds_bpermute_b32 v47, v43, v46
	s_waitcnt lgkmcnt(0)
	v_add_f32_e32 v46, v46, v47
	ds_bpermute_b32 v47, v44, v46
	s_waitcnt lgkmcnt(0)
	v_add_f32_e32 v46, v46, v47
	ds_bpermute_b32 v47, v45, v46
	s_cbranch_vccnz .LBB0_5
	v_lshlrev_b64 v[48:49], 12, v[30:31]
	v_lshl_add_u64 v[48:49], v[34:35], 0, v[48:49]
	global_store_dwordx4 v[48:49], v[22:25], off
	global_store_dwordx4 v[48:49], v[14:17], off offset:1024
	global_store_dwordx4 v[48:49], v[26:29], off offset:2048
	global_store_dwordx4 v[48:49], v[18:21], off offset:3072
	s_branch .LBB0_5

.LBB0_912:
	v_readlane_b32 s0, v253, 8
	v_ashrrev_i32_e32 v0, 6, v216
	s_nop 0
	v_add_u32_e32 v32, s0, v0
	s_movk_i32 s0, 0x4480
	v_cmp_gt_i32_e32 vcc, s0, v32
	s_and_saveexec_b64 s[0:1], vcc
	s_cbranch_execz .LBB0_925
	v_lshlrev_b32_e32 v0, 2, v216
	v_and_b32_e32 v16, 0xfc, v0
	v_lshlrev_b32_e32 v34, 2, v16
	global_load_dwordx4 v[0:3], v34, s[46:47]
	global_load_dwordx4 v[4:7], v34, s[46:47] offset:1024
	global_load_dwordx4 v[8:11], v34, s[46:47] offset:2048
	global_load_dwordx4 v[12:15], v34, s[46:47] offset:3072
	v_cmp_lt_i32_e32 vcc, v227, v219
	v_readlane_b32 s0, v253, 6
	s_waitcnt vmcnt(20)
	v_mov_b32_e32 v35, 0
	v_cndmask_b32_e32 v17, v218, v227, vcc
	v_cmp_lt_i32_e32 vcc, v225, v219
	v_lshlrev_b32_e32 v44, 2, v17
	v_readlane_b32 s1, v253, 7
	v_cndmask_b32_e32 v17, v218, v225, vcc
	v_cmp_lt_i32_e32 vcc, v223, v219
	v_lshlrev_b32_e32 v45, 2, v17
	s_waitcnt vmcnt(18)
	v_lshl_add_u64 v[36:37], s[0:1], 0, v[34:35]
	v_cndmask_b32_e32 v17, v218, v223, vcc
	v_cmp_lt_i32_e32 vcc, v222, v219
	v_lshlrev_b32_e32 v46, 2, v17
	s_movk_i32 s10, 0x407f
	v_cndmask_b32_e32 v17, v218, v222, vcc
	v_cmp_lt_i32_e32 vcc, v221, v219
	v_lshlrev_b32_e32 v47, 2, v17
	s_movk_i32 s11, 0x4080
	v_cndmask_b32_e32 v17, v218, v221, vcc
	v_cmp_lt_i32_e32 vcc, v220, v219
	v_lshlrev_b32_e32 v48, 2, v17
	s_mov_b32 s12, 0xfe03f81
	v_cndmask_b32_e32 v17, v218, v220, vcc
	v_lshlrev_b32_e32 v49, 2, v17
	s_movk_i32 s13, 0xf7f0
	v_mov_b32_e32 v50, 0x358637bd
	s_mov_b32 s14, 0x800000
	s_waitcnt vmcnt(17)
	v_lshlrev_b32_e32 v38, 2, v16
	s_movk_i32 s15, 0x447f
	v_mov_b32_e32 v144, v32
	v_ashrrev_i32_e32 v145, 31, v144
	v_lshlrev_b64 v[144:145], 12, v[144:145]
	v_lshl_add_u64 v[144:145], v[36:37], 0, v[144:145]
	global_load_dwordx4 v[128:131], v[144:145], off
	global_load_dwordx4 v[132:135], v[144:145], off offset:1024
	global_load_dwordx4 v[136:139], v[144:145], off offset:2048
	global_load_dwordx4 v[140:143], v[144:145], off offset:3072
	s_branch .LBB0_915

.LBB0_915:
	v_cmp_lt_i32_e32 vcc, s10, v32
	v_cmp_gt_i32_e64 s[0:1], s11, v32
	s_waitcnt vmcnt(4)
	v_mov_b64_e32 v[40:41], 0
	v_mov_b32_e32 v39, 0
	s_and_saveexec_b64 s[4:5], s[0:1]
	v_mul_hi_i32 v16, v32, s12
	v_lshrrev_b32_e32 v17, 31, v16
	v_ashrrev_i32_e32 v16, 7, v16
	v_add_u32_e32 v16, v16, v17
	v_ashrrev_i32_e32 v17, 31, v16
	v_mad_i32_i24 v39, v16, s13, v32
	v_lshlrev_b64 v[40:41], 23, v[16:17]
	s_or_b64 exec, exec, s[4:5]
	v_ashrrev_i32_e32 v33, 31, v32
	v_lshlrev_b64 v[16:17], 12, v[32:33]
	s_waitcnt vmcnt(4)
	v_lshl_add_u64 v[42:43], v[36:37], 0, v[16:17]
	s_waitcnt vmcnt(0)
	v_mov_b32_e32 v16, v128
	v_mov_b32_e32 v17, v129
	v_mov_b32_e32 v18, v130
	v_mov_b32_e32 v19, v131
	v_mov_b32_e32 v20, v132
	v_mov_b32_e32 v21, v133
	v_mov_b32_e32 v22, v134
	v_mov_b32_e32 v23, v135
	v_mov_b32_e32 v24, v136
	v_mov_b32_e32 v25, v137
	v_mov_b32_e32 v26, v138
	v_mov_b32_e32 v27, v139
	v_mov_b32_e32 v28, v140
	v_mov_b32_e32 v29, v141
	v_mov_b32_e32 v30, v142
	v_mov_b32_e32 v31, v143
	v_add_u32_e32 v144, s81, v32
	v_min_i32_e32 v144, s15, v144
	v_ashrrev_i32_e32 v145, 31, v144
	v_lshlrev_b64 v[144:145], 12, v[144:145]
	v_lshl_add_u64 v[144:145], v[36:37], 0, v[144:145]
	global_load_dwordx4 v[128:131], v[144:145], off
	global_load_dwordx4 v[132:135], v[144:145], off offset:1024
	global_load_dwordx4 v[136:139], v[144:145], off offset:2048
	global_load_dwordx4 v[140:143], v[144:145], off offset:3072
	s_mov_b64 s[0:1], 0
	v_mov_b32_e32 v52, v17
	v_mov_b32_e32 v53, v21
	v_mov_b32_e32 v42, v16
	v_mov_b32_e32 v43, v20
	v_mov_b32_e32 v60, v25
	v_mov_b32_e32 v61, v29
	v_pk_mul_f32 v[52:53], v[52:53], v[52:53]
	v_mov_b32_e32 v54, v18
	v_mov_b32_e32 v55, v22
	v_mov_b32_e32 v58, v24
	v_mov_b32_e32 v59, v28
	v_pk_mul_f32 v[60:61], v[60:61], v[60:61]
	v_pk_fma_f32 v[42:43], v[42:43], v[42:43], v[52:53]
	v_mov_b32_e32 v56, v19
	v_mov_b32_e32 v57, v23
	v_mov_b32_e32 v62, v26
	v_mov_b32_e32 v63, v30
	v_pk_fma_f32 v[52:53], v[58:59], v[58:59], v[60:61]
	v_pk_fma_f32 v[42:43], v[54:55], v[54:55], v[42:43]
	v_mov_b32_e32 v64, v27
	v_mov_b32_e32 v65, v31
	v_pk_fma_f32 v[52:53], v[62:63], v[62:63], v[52:53]
	v_pk_fma_f32 v[42:43], v[56:57], v[56:57], v[42:43]
	v_pk_fma_f32 v[52:53], v[64:65], v[64:65], v[52:53]
	v_add_f32_e32 v33, v42, v43
	v_add_f32_e32 v33, v33, v52
	v_add_f32_e32 v33, v33, v53
	ds_bpermute_b32 v42, v44, v33
	s_waitcnt lgkmcnt(0)
	v_add_f32_e32 v33, v33, v42
	ds_bpermute_b32 v42, v45, v33
	s_waitcnt lgkmcnt(0)
	v_add_f32_e32 v33, v33, v42
	ds_bpermute_b32 v42, v46, v33
	s_waitcnt lgkmcnt(0)
	v_add_f32_e32 v33, v33, v42
	ds_bpermute_b32 v42, v47, v33
	s_waitcnt lgkmcnt(0)
	v_add_f32_e32 v33, v33, v42
	ds_bpermute_b32 v42, v48, v33
	s_waitcnt lgkmcnt(0)
	v_add_f32_e32 v33, v33, v42
	ds_bpermute_b32 v51, v49, v33
	s_and_saveexec_b64 s[4:5], vcc
	s_xor_b64 s[4:5], exec, s[4:5]
	s_cbranch_execz .LBB0_920
	s_mov_b64 s[0:1], exec
	v_add_u32_e32 v34, 0xffffbf80, v32
	s_or_saveexec_b64 s[4:5], s[4:5]
	v_mov_b64_e32 v[42:43], 0x4000000
	s_xor_b64 exec, exec, s[4:5]
	s_cbranch_execnz .LBB0_921
